# wave stagger at the start of the 8 norm + 2 head-norm streaming phases: wave w sleeps w*16*64 cycles once
# speedup vs baseline: 1.0098x; 1.0098x over previous
; #define OPAQUE_IDS int tx = threadIdx.x; int bx = blockIdx.x; asm volatile("" : "+v"(tx), "+s"(bx));
; DI float wave_sum(float v) {
;     v += __shfl_xor(v, 32); v += __shfl_xor(v, 16); v += __shfl_xor(v, 8); v += __shfl_xor(v, 4); v += __shfl_xor(v, 2); v += __shfl_xor(v, 1);
;     return v;
; DI void norm_phase(const Params& p, int layer, int which, bool lat_only, const float* __restrict__ part, int npart, int srcmode) {
;     OPAQUE_IDS
;     const int lane = tx & 63, gw = bx * 8 + (tx >> 6);
;     const float* gain = p.in[6] + ((size_t)layer * 2 + which) * D; const float* mod = (const float*)(p.ws + WS_MOD) + (size_t)layer * 9 * 6144;
;     bf16_t* H = (bf16_t*)(p.ws + WS_H);
;     f32x4 gm[4], sh[4]; int cur_ci = -1;
;     const int nw = gridDim.x * 8;
;     for (int vw = gw; vw < NB * 256; vw += nw)
;     for (int i0 = 0; i0 < 9; i0 += 3) {
;         const int r0 = (vw >> 8) * LT + (vw & 255) + 256 * i0;
;         f32x4 v[3][4]; float ss[3]; bool ok[3];
; #pragma unroll
;         for (int q = 0; q < 3; ++q) {
;             const int row = r0 + 256 * q; const int b = row / LT, pos = row - b * LT;
;             ok[q] = !(lat_only && pos < LC); ss[q] = 0.f;
;             if (ok[q]) {
;                 float* x = resid_row(p, row);
;                 const float* xs = (srcmode == 1 || (srcmode == 2 && pos < LC)) ? (pos < LC ? p.in[2] + ((size_t)(b * LC + pos)) * D : p.in[0] + ((size_t)(b * LL + pos - LC)) * D) : x;
; #pragma unroll
;                 for (int j = 0; j < 4; ++j) v[q][j] = *(const f32x4*)(xs + j * 256 + lane * 4);
.LBB0_215:
	s_or_b64 exec, exec, s[0:1]
	s_add_u32 s0, s68, 0x26da000
	s_addc_u32 s1, s69, 0
	v_writelane_b32 v254, s0, 43
	s_waitcnt lgkmcnt(0)
	v_mov_b32_e32 v0, v252
	v_writelane_b32 v254, s1, 44
	s_mov_b32 s0, s87
	s_barrier
	v_readfirstlane_b32 s98, v252
	s_nop 3
	s_lshr_b32 s98, s98, 6
.Lstg_2:
	s_cmp_eq_u32 s98, 0
	s_cbranch_scc1 .Lstg_2_done
	s_sleep 16
	s_sub_u32 s98, s98, 1
	s_branch .Lstg_2
.Lstg_2_done:
	s_lshl_b32 s93, s70, 3
	v_ashrrev_i32_e32 v1, 6, v0
	v_lshl_add_u32 v81, s0, 3, v1
	s_movk_i32 s0, 0x800
	v_cmp_gt_i32_e32 vcc, s0, v81
	v_mbcnt_lo_u32_b32 v253, -1, 0
	s_and_saveexec_b64 s[6:7], vcc
	s_cbranch_execz .LBB0_272
	v_lshlrev_b32_e32 v0, 2, v0
	v_and_b32_e32 v80, 0xfc, v0
	v_mbcnt_hi_u32_b32 v0, -1, v253
	v_and_b32_e32 v2, 64, v0
	v_xor_b32_e32 v1, 32, v0
	v_add_u32_e32 v2, 64, v2
	v_cmp_lt_i32_e32 vcc, v1, v2
	v_mov_b32_e32 v83, 0
	v_lshlrev_b32_e32 v82, 2, v80
	v_cndmask_b32_e32 v1, v0, v1, vcc
	v_lshlrev_b32_e32 v87, 2, v1
	v_xor_b32_e32 v1, 16, v0
	v_cmp_lt_i32_e32 vcc, v1, v2
	v_readlane_b32 s0, v254, 43
	s_add_u32 s8, s68, 0x800000
	v_cndmask_b32_e32 v1, v0, v1, vcc
	v_lshlrev_b32_e32 v89, 2, v1
	v_xor_b32_e32 v1, 8, v0
	v_cmp_lt_i32_e32 vcc, v1, v2
	v_lshl_add_u64 v[84:85], s[60:61], 0, v[82:83]
	v_lshlrev_b32_e32 v82, 1, v80
	v_cndmask_b32_e32 v1, v0, v1, vcc
	v_lshlrev_b32_e32 v91, 2, v1
	v_xor_b32_e32 v1, 4, v0
	v_cmp_lt_i32_e32 vcc, v1, v2
	v_readlane_b32 s1, v254, 44
	s_addc_u32 s9, s69, 0
	v_cndmask_b32_e32 v1, v0, v1, vcc
	v_lshlrev_b32_e32 v108, 2, v1
	v_xor_b32_e32 v1, 2, v0
	v_cmp_lt_i32_e32 vcc, v1, v2
	v_mov_b32_e32 v95, -1
	s_movk_i32 s14, 0x100
	v_cndmask_b32_e32 v1, v0, v1, vcc
	v_lshlrev_b32_e32 v109, 2, v1
	v_xor_b32_e32 v1, 1, v0
	v_cmp_lt_i32_e32 vcc, v1, v2
	v_or_b32_e32 v86, 0x100, v80
	v_or_b32_e32 v88, 0x200, v80
	v_cndmask_b32_e32 v0, v0, v1, vcc
	v_lshlrev_b32_e32 v110, 2, v0
	v_or_b32_e32 v90, 0x300, v80
	v_lshl_add_u64 v[92:93], s[0:1], 0, v[82:83]
	s_mov_b64 s[10:11], 0
	s_movk_i32 s15, 0xff
	s_mov_b32 s28, 0x38e38e39
	s_movk_i32 s29, 0xf700
	s_movk_i32 s30, 0xff00
	s_mov_b64 s[12:13], 0x1000
	v_mov_b32_e32 v111, 0x358637bd
	s_mov_b32 s31, 0x800000
	s_movk_i32 s34, 0x7ff
	s_branch .LBB0_218

; #define OPAQUE_IDS int tx = threadIdx.x; int bx = blockIdx.x; asm volatile("" : "+v"(tx), "+s"(bx));
; DI unsigned xb_ld(unsigned* p)              { return __hip_atomic_load(p, __ATOMIC_RELAXED, __HIP_MEMORY_SCOPE_AGENT); }
; #define XB_SPIN(cond, bar) do { unsigned _sp = 0; while (cond) { __builtin_amdgcn_s_sleep(1); \
;     if ((++_sp & 255u) == 0u) { if (xb_ld(&(bar)[XB_TMO])) break; if (_sp > XB_SPIN_CAP) { atomicAdd(&(bar)[XB_TMO], 1u); break; } } } } while (0)
; DI void norm_phase(const Params& p, int layer, int which, bool lat_only, const float* __restrict__ part, int npart, int srcmode) {
;     OPAQUE_IDS
;     const int lane = tx & 63, gw = bx * 8 + (tx >> 6);
; DI void xcd_barrier(const XcdBarrier& b) {
;     ...
;             XB_SPIN(xb_ld(&bar[XB_XGEN(b.x)]) == gen, bar);
;             __builtin_amdgcn_fence(__ATOMIC_ACQUIRE, "agent");
;             asm volatile("s_waitcnt vmcnt(0)" ::: "memory");
;         }
;     }
;     __syncthreads();
.LBB0_627:
	s_or_b64 exec, exec, s[0:1]
	s_waitcnt lgkmcnt(0)
	v_mov_b32_e32 v0, v252
	s_mov_b32 s0, s87
	s_barrier
	v_readfirstlane_b32 s98, v252
	s_nop 3
	s_lshr_b32 s98, s98, 6

; #define OPAQUE_IDS int tx = threadIdx.x; int bx = blockIdx.x; asm volatile("" : "+v"(tx), "+s"(bx));
; DI float wave_sum(float v) {
;     v += __shfl_xor(v, 32); v += __shfl_xor(v, 16); v += __shfl_xor(v, 8); v += __shfl_xor(v, 4); v += __shfl_xor(v, 2); v += __shfl_xor(v, 1);
;     return v;
; DI void norm_phase(const Params& p, int layer, int which, bool lat_only, const float* __restrict__ part, int npart, int srcmode) {
;     OPAQUE_IDS
;     const int lane = tx & 63, gw = bx * 8 + (tx >> 6);
;     const float* gain = p.in[6] + ((size_t)layer * 2 + which) * D; const float* mod = (const float*)(p.ws + WS_MOD) + (size_t)layer * 9 * 6144;
;     bf16_t* H = (bf16_t*)(p.ws + WS_H);
;     f32x4 gm[4], sh[4]; int cur_ci = -1;
;     const int nw = gridDim.x * 8;
;     for (int vw = gw; vw < NB * 256; vw += nw)
;     for (int i0 = 0; i0 < 9; i0 += 3) {
;         const int r0 = (vw >> 8) * LT + (vw & 255) + 256 * i0;
;         f32x4 v[3][4]; float ss[3]; bool ok[3];
; #pragma unroll
;         for (int q = 0; q < 3; ++q) {
;             const int row = r0 + 256 * q; const int b = row / LT, pos = row - b * LT;
;             ok[q] = !(lat_only && pos < LC); ss[q] = 0.f;
;             if (ok[q]) {
;                 float* x = resid_row(p, row);
;                 const float* xs = (srcmode == 1 || (srcmode == 2 && pos < LC)) ? (pos < LC ? p.in[2] + ((size_t)(b * LC + pos)) * D : p.in[0] + ((size_t)(b * LL + pos - LC)) * D) : x;
; #pragma unroll
;                 for (int j = 0; j < 4; ++j) v[q][j] = *(const f32x4*)(xs + j * 256 + lane * 4);
.Lstg_6_done:
	s_nop 0
	v_ashrrev_i32_e32 v1, 6, v0
	v_lshl_add_u32 v81, s0, 3, v1
	s_movk_i32 s0, 0x800
	v_cmp_gt_i32_e32 vcc, s0, v81
	s_and_saveexec_b64 s[6:7], vcc
	s_cbranch_execz .LBB0_702
	v_lshlrev_b32_e32 v0, 2, v0
	v_and_b32_e32 v80, 0xfc, v0
	v_mbcnt_hi_u32_b32 v0, -1, v253
	v_and_b32_e32 v2, 64, v0
	v_xor_b32_e32 v1, 32, v0
	v_add_u32_e32 v2, 64, v2
	v_cmp_lt_i32_e32 vcc, v1, v2
	s_add_u32 s0, s60, 0x1000
	s_addc_u32 s1, s61, 0
	v_cndmask_b32_e32 v1, v0, v1, vcc
	v_lshlrev_b32_e32 v89, 2, v1
	v_xor_b32_e32 v1, 16, v0
	v_cmp_lt_i32_e32 vcc, v1, v2
	v_mov_b32_e32 v83, 0
	v_lshlrev_b32_e32 v82, 2, v80
	v_cndmask_b32_e32 v1, v0, v1, vcc
	v_lshlrev_b32_e32 v93, 2, v1
	v_xor_b32_e32 v1, 8, v0
	v_cmp_lt_i32_e32 vcc, v1, v2
	v_or_b32_e32 v88, 0x100, v80
	v_lshl_add_u64 v[84:85], s[96:97], 0, v[82:83]
	v_cndmask_b32_e32 v1, v0, v1, vcc
	v_lshlrev_b32_e32 v97, 2, v1
	v_xor_b32_e32 v1, 4, v0
	v_cmp_lt_i32_e32 vcc, v1, v2
	v_lshl_add_u64 v[86:87], s[0:1], 0, v[82:83]
	v_lshlrev_b32_e32 v82, 2, v88
	v_cndmask_b32_e32 v1, v0, v1, vcc
	v_lshlrev_b32_e32 v120, 2, v1
	v_xor_b32_e32 v1, 2, v0
	v_cmp_lt_i32_e32 vcc, v1, v2
	v_or_b32_e32 v92, 0x200, v80
	v_lshl_add_u64 v[90:91], s[0:1], 0, v[82:83]
	v_cndmask_b32_e32 v1, v0, v1, vcc
	v_lshlrev_b32_e32 v82, 2, v92
	v_or_b32_e32 v96, 0x300, v80
	v_lshlrev_b32_e32 v121, 2, v1
	v_xor_b32_e32 v1, 1, v0
	v_lshl_add_u64 v[94:95], s[0:1], 0, v[82:83]
	v_lshlrev_b32_e32 v82, 2, v96
	v_cmp_lt_i32_e32 vcc, v1, v2
	v_lshl_add_u64 v[98:99], s[0:1], 0, v[82:83]
	v_readlane_b32 s0, v254, 43
	v_cndmask_b32_e32 v0, v0, v1, vcc
	s_add_u32 s10, s68, 0x803000
	v_lshlrev_b32_e32 v82, 1, v80
	v_readlane_b32 s1, v254, 44
	s_mov_b64 s[8:9], 0x1000
	v_mov_b32_e32 v109, -1
	v_lshlrev_b32_e32 v122, 2, v0
	s_addc_u32 s11, s69, 0
	s_movk_i32 s28, 0x100
	v_lshl_add_u64 v[100:101], s[0:1], 0, v[82:83]
	s_mov_b64 s[12:13], 0
	s_movk_i32 s29, 0xff
	s_mov_b32 s30, 0x38e38e39
	s_movk_i32 s31, 0xf700
	s_movk_i32 s34, 0xff00
	s_mov_b32 s35, 0x800000
	s_mov_b32 s36, 0x1000000
	s_mov_b32 s37, 0x1800000
	v_mov_b32_e32 v123, 0x358637bd
	s_movk_i32 s38, 0x7ff
	s_branch .LBB0_630

; #define OPAQUE_IDS int tx = threadIdx.x; int bx = blockIdx.x; asm volatile("" : "+v"(tx), "+s"(bx));
; DI unsigned xb_ld(unsigned* p)              { return __hip_atomic_load(p, __ATOMIC_RELAXED, __HIP_MEMORY_SCOPE_AGENT); }
; #define XB_SPIN(cond, bar) do { unsigned _sp = 0; while (cond) { __builtin_amdgcn_s_sleep(1); \
;     if ((++_sp & 255u) == 0u) { if (xb_ld(&(bar)[XB_TMO])) break; if (_sp > XB_SPIN_CAP) { atomicAdd(&(bar)[XB_TMO], 1u); break; } } } } while (0)
; DI void norm_phase(const Params& p, int layer, int which, bool lat_only, const float* __restrict__ part, int npart, int srcmode) {
;     OPAQUE_IDS
;     const int lane = tx & 63, gw = bx * 8 + (tx >> 6);
; DI void xcd_barrier(const XcdBarrier& b) {
;     ...
;             XB_SPIN(xb_ld(&bar[XB_XGEN(b.x)]) == gen, bar);
;             __builtin_amdgcn_fence(__ATOMIC_ACQUIRE, "agent");
;             asm volatile("s_waitcnt vmcnt(0)" ::: "memory");
;         }
;     }
;     __syncthreads();
.LBB0_955:
	v_readlane_b32 s2, v254, 1
	v_mov_b32_e32 v0, v252
	s_mov_b32 s0, s87
	v_readlane_b32 s3, v254, 2
	s_barrier
	v_readfirstlane_b32 s98, v252
	s_nop 3
	s_lshr_b32 s98, s98, 6

; #define OPAQUE_IDS int tx = threadIdx.x; int bx = blockIdx.x; asm volatile("" : "+v"(tx), "+s"(bx));
; DI float wave_sum(float v) {
;     v += __shfl_xor(v, 32); v += __shfl_xor(v, 16); v += __shfl_xor(v, 8); v += __shfl_xor(v, 4); v += __shfl_xor(v, 2); v += __shfl_xor(v, 1);
;     return v;
; DI void norm_phase(const Params& p, int layer, int which, bool lat_only, const float* __restrict__ part, int npart, int srcmode) {
;     OPAQUE_IDS
;     const int lane = tx & 63, gw = bx * 8 + (tx >> 6);
;     const float* gain = p.in[6] + ((size_t)layer * 2 + which) * D; const float* mod = (const float*)(p.ws + WS_MOD) + (size_t)layer * 9 * 6144;
;     bf16_t* H = (bf16_t*)(p.ws + WS_H);
;     f32x4 gm[4], sh[4]; int cur_ci = -1;
;     const int nw = gridDim.x * 8;
;     for (int vw = gw; vw < NB * 256; vw += nw)
;     for (int i0 = 0; i0 < 9; i0 += 3) {
;         const int r0 = (vw >> 8) * LT + (vw & 255) + 256 * i0;
;         f32x4 v[3][4]; float ss[3]; bool ok[3];
; #pragma unroll
;         for (int q = 0; q < 3; ++q) {
;             const int row = r0 + 256 * q; const int b = row / LT, pos = row - b * LT;
;             ok[q] = !(lat_only && pos < LC); ss[q] = 0.f;
;             if (ok[q]) {
;                 float* x = resid_row(p, row);
;                 const float* xs = (srcmode == 1 || (srcmode == 2 && pos < LC)) ? (pos < LC ? p.in[2] + ((size_t)(b * LC + pos)) * D : p.in[0] + ((size_t)(b * LL + pos - LC)) * D) : x;
; #pragma unroll
;                 for (int j = 0; j < 4; ++j) v[q][j] = *(const f32x4*)(xs + j * 256 + lane * 4);
;                 if (part != nullptr && pos < LC) {
;                     f32x4 a[4];
; #pragma unroll
;                     for (int j = 0; j < 4; ++j) a[j] = (f32x4){0.f, 0.f, 0.f, 0.f};
;                     const float* pp = part + (size_t)(b * LC + pos) * D + lane * 4;
;                     for (int s = 0; s < npart; ++s) {
; #pragma unroll
;                         for (int j = 0; j < 4; ++j) a[j] += *(const f32x4*)(pp + (size_t)s * NB * LC * D + j * 256); }
.Lstg_9_done:
	s_load_dword s1, s[2:3], 0x10
	s_nop 0
	s_load_dword s2, s[2:3], 0x0
	v_ashrrev_i32_e32 v1, 6, v0
	v_lshl_add_u32 v81, s0, 3, v1
	s_waitcnt lgkmcnt(0)
	s_lshr_b32 s0, s1, 16
	s_cmp_lg_u32 s0, 0
	s_cselect_b64 s[0:1], -1, 0
	s_cmp_lg_u64 s[0:1], 0
	s_addc_u32 s26, s2, 0
	s_movk_i32 s0, 0x800
	s_lshl_b32 s6, s26, 3
	v_cmp_gt_i32_e32 vcc, s0, v81
	s_and_saveexec_b64 s[8:9], vcc
	s_cbranch_execz .LBB0_1030
	v_lshlrev_b32_e32 v0, 2, v0
	v_and_b32_e32 v80, 0xfc, v0
	v_mbcnt_hi_u32_b32 v0, -1, v253
	v_and_b32_e32 v2, 64, v0
	v_xor_b32_e32 v1, 32, v0
	v_add_u32_e32 v2, 64, v2
	v_cmp_lt_i32_e32 vcc, v1, v2
	s_add_u32 s0, s60, 0x2000
	s_addc_u32 s1, s61, 0
	v_cndmask_b32_e32 v1, v0, v1, vcc
	v_lshlrev_b32_e32 v89, 2, v1
	v_xor_b32_e32 v1, 16, v0
	v_cmp_lt_i32_e32 vcc, v1, v2
	v_mov_b32_e32 v83, 0
	v_lshlrev_b32_e32 v82, 2, v80
	v_cndmask_b32_e32 v1, v0, v1, vcc
	v_lshlrev_b32_e32 v93, 2, v1
	v_xor_b32_e32 v1, 8, v0
	v_cmp_lt_i32_e32 vcc, v1, v2
	v_or_b32_e32 v88, 0x100, v80
	v_lshl_add_u64 v[84:85], s[28:29], 0, v[82:83]
	v_cndmask_b32_e32 v1, v0, v1, vcc
	v_lshlrev_b32_e32 v97, 2, v1
	v_xor_b32_e32 v1, 4, v0
	v_cmp_lt_i32_e32 vcc, v1, v2
	v_lshl_add_u64 v[86:87], s[0:1], 0, v[82:83]
	v_lshlrev_b32_e32 v82, 2, v88
	v_cndmask_b32_e32 v1, v0, v1, vcc
	v_lshlrev_b32_e32 v120, 2, v1
	v_xor_b32_e32 v1, 2, v0
	v_cmp_lt_i32_e32 vcc, v1, v2
	v_or_b32_e32 v92, 0x200, v80
	v_lshl_add_u64 v[90:91], s[0:1], 0, v[82:83]
	v_cndmask_b32_e32 v1, v0, v1, vcc
	v_lshlrev_b32_e32 v121, 2, v1
	v_xor_b32_e32 v1, 1, v0
	v_lshlrev_b32_e32 v82, 2, v92
	v_or_b32_e32 v96, 0x300, v80
	v_cmp_lt_i32_e32 vcc, v1, v2
	v_lshl_add_u64 v[94:95], s[0:1], 0, v[82:83]
	v_lshlrev_b32_e32 v82, 2, v96
	s_add_u32 s10, s68, 0x836000
	v_cndmask_b32_e32 v0, v0, v1, vcc
	v_lshl_add_u64 v[98:99], s[0:1], 0, v[82:83]
	v_lshlrev_b32_e32 v82, 1, v80
	s_addc_u32 s11, s69, 0
	v_mov_b32_e32 v109, -1
	v_lshlrev_b32_e32 v122, 2, v0
	s_movk_i32 s7, 0x100
	v_lshl_add_u64 v[100:101], s[16:17], 0, v[82:83]
	s_mov_b64 s[12:13], 0
	s_movk_i32 s34, 0xff
	s_mov_b32 s35, 0x38e38e39
	s_movk_i32 s36, 0xf700
	s_movk_i32 s37, 0xff00
	s_mov_b32 s38, 0x800000
	s_mov_b32 s39, 0x1000000
	s_mov_b32 s40, 0x1800000
	s_brev_b32 s41, 64
	s_mov_b32 s42, 0x2800000
	s_mov_b32 s43, 0x3000000
	s_mov_b32 s44, 0x3800000
	s_mov_b64 s[30:31], 0x1000
	v_mov_b32_e32 v123, 0x358637bd
	s_movk_i32 s45, 0x7ff
	s_branch .LBB0_958

; #define OPAQUE_IDS int tx = threadIdx.x; int bx = blockIdx.x; asm volatile("" : "+v"(tx), "+s"(bx));
; DI unsigned xb_ld(unsigned* p)              { return __hip_atomic_load(p, __ATOMIC_RELAXED, __HIP_MEMORY_SCOPE_AGENT); }
; #define XB_SPIN(cond, bar) do { unsigned _sp = 0; while (cond) { __builtin_amdgcn_s_sleep(1); \
;     if ((++_sp & 255u) == 0u) { if (xb_ld(&(bar)[XB_TMO])) break; if (_sp > XB_SPIN_CAP) { atomicAdd(&(bar)[XB_TMO], 1u); break; } } } } while (0)
; template <int MODE>
; DI void headnorm_phase(const Params& p, const bf16_t* __restrict__ A0, const bf16_t* __restrict__ A1, const bf16_t* __restrict__ G, const float* gain, float lam, float outscale) {
;     OPAQUE_IDS
;     const int lane = tx & 63, gw = bx * 8 + (tx >> 6), nw = gridDim.x * 8;
;     bf16_t* H = (bf16_t*)(p.ws + WS_H); const int hh = lane >> 3, d0 = (lane & 7) * 16;
;     for (int row = gw; row < T; row += nw) {
; DI void xcd_barrier(const XcdBarrier& b) {
;     ...
;             XB_SPIN(xb_ld(&bar[XB_XGEN(b.x)]) == gen, bar);
;             __builtin_amdgcn_fence(__ATOMIC_ACQUIRE, "agent");
;             asm volatile("s_waitcnt vmcnt(0)" ::: "memory");
;         }
;     }
;     __syncthreads();
.LBB0_1382:
	s_or_b64 exec, exec, s[0:1]
	v_mov_b32_e32 v2, 0
	v_readlane_b32 s36, v254, 7
	s_mov_b64 s[0:1], 0
	s_waitcnt lgkmcnt(0)
	v_mov_b32_e32 v0, 0
	v_mov_b32_e32 v1, v2
	v_readlane_b32 s48, v254, 19
	v_readlane_b32 s49, v254, 20
	s_barrier
	v_readfirstlane_b32 s98, v252
	s_nop 3
	s_lshr_b32 s98, s98, 6

; #define OPAQUE_IDS int tx = threadIdx.x; int bx = blockIdx.x; asm volatile("" : "+v"(tx), "+s"(bx));
; template <int MODE>
; DI void headnorm_phase(const Params& p, const bf16_t* __restrict__ A0, const bf16_t* __restrict__ A1, const bf16_t* __restrict__ G, const float* gain, float lam, float outscale) {
;     OPAQUE_IDS
;     const int lane = tx & 63, gw = bx * 8 + (tx >> 6), nw = gridDim.x * 8;
;     bf16_t* H = (bf16_t*)(p.ws + WS_H); const int hh = lane >> 3, d0 = (lane & 7) * 16;
;     for (int row = gw; row < T; row += nw) {
.Lstg_13_done:
	v_readlane_b32 s37, v254, 8
	v_readlane_b32 s38, v254, 9
	v_readlane_b32 s39, v254, 10
	v_readlane_b32 s40, v254, 11
	v_readlane_b32 s41, v254, 12
	v_readlane_b32 s42, v254, 13
	v_readlane_b32 s43, v254, 14
	v_readlane_b32 s44, v254, 15
	v_readlane_b32 s45, v254, 16
	v_readlane_b32 s46, v254, 17
	v_readlane_b32 s47, v254, 18
	v_readlane_b32 s50, v254, 21
	v_readlane_b32 s51, v254, 22

; #define OPAQUE_IDS int tx = threadIdx.x; int bx = blockIdx.x; asm volatile("" : "+v"(tx), "+s"(bx));
; DI unsigned xb_ld(unsigned* p)              { return __hip_atomic_load(p, __ATOMIC_RELAXED, __HIP_MEMORY_SCOPE_AGENT); }
; #define XB_SPIN(cond, bar) do { unsigned _sp = 0; while (cond) { __builtin_amdgcn_s_sleep(1); \
;     if ((++_sp & 255u) == 0u) { if (xb_ld(&(bar)[XB_TMO])) break; if (_sp > XB_SPIN_CAP) { atomicAdd(&(bar)[XB_TMO], 1u); break; } } } } while (0)
; DI void norm_phase(const Params& p, int layer, int which, bool lat_only, const float* __restrict__ part, int npart, int srcmode) {
;     OPAQUE_IDS
;     const int lane = tx & 63, gw = bx * 8 + (tx >> 6);
; DI void xcd_barrier(const XcdBarrier& b) {
;     ...
;             XB_SPIN(xb_ld(&bar[XB_XGEN(b.x)]) == gen, bar);
;             __builtin_amdgcn_fence(__ATOMIC_ACQUIRE, "agent");
;             asm volatile("s_waitcnt vmcnt(0)" ::: "memory");
;         }
;     }
;     __syncthreads();
.LBB0_1558:
	s_or_b64 exec, exec, s[0:1]
	s_mov_b32 s0, s87
	s_waitcnt lgkmcnt(0)
	v_mov_b32_e32 v0, v252
	s_barrier
	v_readfirstlane_b32 s98, v252
	s_nop 3
	s_lshr_b32 s98, s98, 6

; #define OPAQUE_IDS int tx = threadIdx.x; int bx = blockIdx.x; asm volatile("" : "+v"(tx), "+s"(bx));
; DI float wave_sum(float v) {
;     v += __shfl_xor(v, 32); v += __shfl_xor(v, 16); v += __shfl_xor(v, 8); v += __shfl_xor(v, 4); v += __shfl_xor(v, 2); v += __shfl_xor(v, 1);
;     return v;
; DI void norm_phase(const Params& p, int layer, int which, bool lat_only, const float* __restrict__ part, int npart, int srcmode) {
;     OPAQUE_IDS
;     const int lane = tx & 63, gw = bx * 8 + (tx >> 6);
;     const float* gain = p.in[6] + ((size_t)layer * 2 + which) * D; const float* mod = (const float*)(p.ws + WS_MOD) + (size_t)layer * 9 * 6144;
;     bf16_t* H = (bf16_t*)(p.ws + WS_H);
;     f32x4 gm[4], sh[4]; int cur_ci = -1;
;     const int nw = gridDim.x * 8;
;     for (int vw = gw; vw < NB * 256; vw += nw)
;     for (int i0 = 0; i0 < 9; i0 += 3) {
;         const int r0 = (vw >> 8) * LT + (vw & 255) + 256 * i0;
;         f32x4 v[3][4]; float ss[3]; bool ok[3];
; #pragma unroll
;         for (int q = 0; q < 3; ++q) {
;             const int row = r0 + 256 * q; const int b = row / LT, pos = row - b * LT;
;             ok[q] = !(lat_only && pos < LC); ss[q] = 0.f;
;             if (ok[q]) {
;                 float* x = resid_row(p, row);
;                 const float* xs = (srcmode == 1 || (srcmode == 2 && pos < LC)) ? (pos < LC ? p.in[2] + ((size_t)(b * LC + pos)) * D : p.in[0] + ((size_t)(b * LL + pos - LC)) * D) : x;
; #pragma unroll
;                 for (int j = 0; j < 4; ++j) v[q][j] = *(const f32x4*)(xs + j * 256 + lane * 4);
;                 if (part != nullptr && pos < LC) {
;                     f32x4 a[4];
; #pragma unroll
;                     for (int j = 0; j < 4; ++j) a[j] = (f32x4){0.f, 0.f, 0.f, 0.f};
;                     const float* pp = part + (size_t)(b * LC + pos) * D + lane * 4;
;                     for (int s = 0; s < npart; ++s) {
; #pragma unroll
;                         for (int j = 0; j < 4; ++j) a[j] += *(const f32x4*)(pp + (size_t)s * NB * LC * D + j * 256); }
.Lstg_15_done:
	s_nop 0
	v_ashrrev_i32_e32 v1, 6, v0
	v_lshl_add_u32 v81, s0, 3, v1
	s_movk_i32 s0, 0x800
	v_cmp_gt_i32_e32 vcc, s0, v81
	s_and_saveexec_b64 s[8:9], vcc
	s_cbranch_execz .LBB0_1633
	v_lshlrev_b32_e32 v0, 2, v0
	v_and_b32_e32 v80, 0xfc, v0
	v_mbcnt_hi_u32_b32 v0, -1, v253
	v_and_b32_e32 v2, 64, v0
	v_xor_b32_e32 v1, 32, v0
	v_add_u32_e32 v2, 64, v2
	v_cmp_lt_i32_e32 vcc, v1, v2
	s_add_u32 s0, s60, 0x3000
	s_addc_u32 s1, s61, 0
	v_cndmask_b32_e32 v1, v0, v1, vcc
	v_lshlrev_b32_e32 v89, 2, v1
	v_xor_b32_e32 v1, 16, v0
	v_cmp_lt_i32_e32 vcc, v1, v2
	v_mov_b32_e32 v83, 0
	v_lshlrev_b32_e32 v82, 2, v80
	v_cndmask_b32_e32 v1, v0, v1, vcc
	v_lshlrev_b32_e32 v93, 2, v1
	v_xor_b32_e32 v1, 8, v0
	v_cmp_lt_i32_e32 vcc, v1, v2
	v_or_b32_e32 v88, 0x100, v80
	v_lshl_add_u64 v[84:85], s[96:97], 0, v[82:83]
	v_cndmask_b32_e32 v1, v0, v1, vcc
	v_lshlrev_b32_e32 v97, 2, v1
	v_xor_b32_e32 v1, 4, v0
	v_cmp_lt_i32_e32 vcc, v1, v2
	v_lshl_add_u64 v[86:87], s[0:1], 0, v[82:83]
	v_lshlrev_b32_e32 v82, 2, v88
	v_cndmask_b32_e32 v1, v0, v1, vcc
	v_lshlrev_b32_e32 v120, 2, v1
	v_xor_b32_e32 v1, 2, v0
	v_cmp_lt_i32_e32 vcc, v1, v2
	v_or_b32_e32 v92, 0x200, v80
	v_lshl_add_u64 v[90:91], s[0:1], 0, v[82:83]
	v_cndmask_b32_e32 v1, v0, v1, vcc
	v_lshlrev_b32_e32 v121, 2, v1
	v_xor_b32_e32 v1, 1, v0
	v_lshlrev_b32_e32 v82, 2, v92
	v_or_b32_e32 v96, 0x300, v80
	v_cmp_lt_i32_e32 vcc, v1, v2
	v_lshl_add_u64 v[94:95], s[0:1], 0, v[82:83]
	v_lshlrev_b32_e32 v82, 2, v96
	v_cndmask_b32_e32 v0, v0, v1, vcc
	s_add_u32 s10, s68, 0x839000
	v_lshl_add_u64 v[98:99], s[0:1], 0, v[82:83]
	v_lshlrev_b32_e32 v82, 1, v80
	v_mov_b32_e32 v107, -1
	v_lshlrev_b32_e32 v122, 2, v0
	s_addc_u32 s11, s69, 0
	s_movk_i32 s7, 0x100
	v_lshl_add_u64 v[100:101], s[16:17], 0, v[82:83]
	s_mov_b64 s[12:13], 0
	s_movk_i32 s34, 0xff
	s_mov_b32 s35, 0x38e38e39
	s_movk_i32 s36, 0xf700
	s_movk_i32 s37, 0xff00
	s_mov_b32 s38, 0x800000
	s_mov_b32 s39, 0x1000000
	s_mov_b32 s40, 0x1800000
	s_mov_b64 s[30:31], 0x1000
	v_mov_b32_e32 v123, 0x358637bd
	s_movk_i32 s41, 0x7ff
	s_branch .LBB0_1561

; #define OPAQUE_IDS int tx = threadIdx.x; int bx = blockIdx.x; asm volatile("" : "+v"(tx), "+s"(bx));
; DI unsigned xb_ld(unsigned* p)              { return __hip_atomic_load(p, __ATOMIC_RELAXED, __HIP_MEMORY_SCOPE_AGENT); }
; #define XB_SPIN(cond, bar) do { unsigned _sp = 0; while (cond) { __builtin_amdgcn_s_sleep(1); \
;     if ((++_sp & 255u) == 0u) { if (xb_ld(&(bar)[XB_TMO])) break; if (_sp > XB_SPIN_CAP) { atomicAdd(&(bar)[XB_TMO], 1u); break; } } } } while (0)
; DI void norm_phase(const Params& p, int layer, int which, bool lat_only, const float* __restrict__ part, int npart, int srcmode) {
;     OPAQUE_IDS
;     const int lane = tx & 63, gw = bx * 8 + (tx >> 6);
; DI void xcd_barrier(const XcdBarrier& b) {
;     ...
;             XB_SPIN(xb_ld(&bar[XB_XGEN(b.x)]) == gen, bar);
;             __builtin_amdgcn_fence(__ATOMIC_ACQUIRE, "agent");
;             asm volatile("s_waitcnt vmcnt(0)" ::: "memory");
;         }
;     }
;     __syncthreads();
.LBB0_1886:
	v_readlane_b32 s2, v254, 1
	s_mov_b32 s0, s87
	v_mov_b32_e32 v0, v252
	v_readlane_b32 s3, v254, 2
	s_barrier
	v_readfirstlane_b32 s98, v252
	s_nop 3
	s_lshr_b32 s98, s98, 6

; #define OPAQUE_IDS int tx = threadIdx.x; int bx = blockIdx.x; asm volatile("" : "+v"(tx), "+s"(bx));
; DI float wave_sum(float v) {
;     v += __shfl_xor(v, 32); v += __shfl_xor(v, 16); v += __shfl_xor(v, 8); v += __shfl_xor(v, 4); v += __shfl_xor(v, 2); v += __shfl_xor(v, 1);
;     return v;
; DI void norm_phase(const Params& p, int layer, int which, bool lat_only, const float* __restrict__ part, int npart, int srcmode) {
;     OPAQUE_IDS
;     const int lane = tx & 63, gw = bx * 8 + (tx >> 6);
;     const float* gain = p.in[6] + ((size_t)layer * 2 + which) * D; const float* mod = (const float*)(p.ws + WS_MOD) + (size_t)layer * 9 * 6144;
;     bf16_t* H = (bf16_t*)(p.ws + WS_H);
;     f32x4 gm[4], sh[4]; int cur_ci = -1;
;     const int nw = gridDim.x * 8;
;     for (int vw = gw; vw < NB * 256; vw += nw)
;     for (int i0 = 0; i0 < 9; i0 += 3) {
;         const int r0 = (vw >> 8) * LT + (vw & 255) + 256 * i0;
;         f32x4 v[3][4]; float ss[3]; bool ok[3];
; #pragma unroll
;         for (int q = 0; q < 3; ++q) {
;             const int row = r0 + 256 * q; const int b = row / LT, pos = row - b * LT;
;             ok[q] = !(lat_only && pos < LC); ss[q] = 0.f;
;             if (ok[q]) {
;                 float* x = resid_row(p, row);
;                 const float* xs = (srcmode == 1 || (srcmode == 2 && pos < LC)) ? (pos < LC ? p.in[2] + ((size_t)(b * LC + pos)) * D : p.in[0] + ((size_t)(b * LL + pos - LC)) * D) : x;
; #pragma unroll
;                 for (int j = 0; j < 4; ++j) v[q][j] = *(const f32x4*)(xs + j * 256 + lane * 4);
;                 if (part != nullptr && pos < LC) {
;                     f32x4 a[4];
; #pragma unroll
;                     for (int j = 0; j < 4; ++j) a[j] = (f32x4){0.f, 0.f, 0.f, 0.f};
;                     const float* pp = part + (size_t)(b * LC + pos) * D + lane * 4;
;                     for (int s = 0; s < npart; ++s) {
; #pragma unroll
;                         for (int j = 0; j < 4; ++j) a[j] += *(const f32x4*)(pp + (size_t)s * NB * LC * D + j * 256); }
.Lstg_18_done:
	s_load_dword s1, s[2:3], 0x10
	s_load_dword s31, s[2:3], 0x0
	v_ashrrev_i32_e32 v1, 6, v0
	v_lshl_add_u32 v81, s0, 3, v1
	s_waitcnt lgkmcnt(0)
	s_lshr_b32 s0, s1, 16
	s_cmp_lg_u32 s0, 0
	s_cselect_b64 s[12:13], -1, 0
	s_cmp_lg_u64 s[12:13], 0
	s_addc_u32 s26, s31, 0
	s_movk_i32 s0, 0x800
	s_lshl_b32 s30, s26, 3
	v_cmp_gt_i32_e32 vcc, s0, v81
	s_and_saveexec_b64 s[6:7], vcc
	s_cbranch_execz .LBB0_1961
	v_lshlrev_b32_e32 v0, 2, v0
	v_and_b32_e32 v80, 0xfc, v0
	v_mbcnt_hi_u32_b32 v0, -1, v253
	v_and_b32_e32 v2, 64, v0
	v_xor_b32_e32 v1, 32, v0
	v_add_u32_e32 v2, 64, v2
	v_cmp_lt_i32_e32 vcc, v1, v2
	s_add_u32 s0, s60, 0x4000
	s_addc_u32 s1, s61, 0
	v_cndmask_b32_e32 v1, v0, v1, vcc
	v_lshlrev_b32_e32 v89, 2, v1
	v_xor_b32_e32 v1, 16, v0
	v_cmp_lt_i32_e32 vcc, v1, v2
	v_mov_b32_e32 v83, 0
	v_lshlrev_b32_e32 v82, 2, v80
	v_cndmask_b32_e32 v1, v0, v1, vcc
	v_lshlrev_b32_e32 v93, 2, v1
	v_xor_b32_e32 v1, 8, v0
	v_cmp_lt_i32_e32 vcc, v1, v2
	v_or_b32_e32 v88, 0x100, v80
	v_lshl_add_u64 v[84:85], s[28:29], 0, v[82:83]
	v_cndmask_b32_e32 v1, v0, v1, vcc
	v_lshlrev_b32_e32 v97, 2, v1
	v_xor_b32_e32 v1, 4, v0
	v_cmp_lt_i32_e32 vcc, v1, v2
	v_lshl_add_u64 v[86:87], s[0:1], 0, v[82:83]
	v_lshlrev_b32_e32 v82, 2, v88
	v_cndmask_b32_e32 v1, v0, v1, vcc
	v_lshlrev_b32_e32 v120, 2, v1
	v_xor_b32_e32 v1, 2, v0
	v_cmp_lt_i32_e32 vcc, v1, v2
	v_or_b32_e32 v92, 0x200, v80
	v_lshl_add_u64 v[90:91], s[0:1], 0, v[82:83]
	v_cndmask_b32_e32 v1, v0, v1, vcc
	v_lshlrev_b32_e32 v121, 2, v1
	v_xor_b32_e32 v1, 1, v0
	v_lshlrev_b32_e32 v82, 2, v92
	v_or_b32_e32 v96, 0x300, v80
	v_cmp_lt_i32_e32 vcc, v1, v2
	v_lshl_add_u64 v[94:95], s[0:1], 0, v[82:83]
	v_lshlrev_b32_e32 v82, 2, v96
	s_add_u32 s8, s68, 0x86c000
	v_cndmask_b32_e32 v0, v0, v1, vcc
	v_lshl_add_u64 v[98:99], s[0:1], 0, v[82:83]
	v_lshlrev_b32_e32 v82, 1, v80
	s_addc_u32 s9, s69, 0
	v_mov_b32_e32 v109, -1
	v_lshlrev_b32_e32 v122, 2, v0
	s_movk_i32 s36, 0x100
	v_lshl_add_u64 v[100:101], s[16:17], 0, v[82:83]
	s_mov_b64 s[10:11], 0
	s_movk_i32 s37, 0xff
	s_mov_b32 s38, 0x38e38e39
	s_movk_i32 s39, 0xf700
	s_movk_i32 s40, 0xff00
	s_mov_b32 s41, 0x800000
	s_mov_b32 s42, 0x1000000
	s_mov_b32 s43, 0x1800000
	s_brev_b32 s44, 64
	s_mov_b32 s45, 0x2800000
	s_mov_b32 s46, 0x3000000
	s_mov_b32 s47, 0x3800000
	s_mov_b64 s[34:35], 0x1000
	v_mov_b32_e32 v123, 0x358637bd
	s_movk_i32 s48, 0x7ff
	s_branch .LBB0_1889

; #define OPAQUE_IDS int tx = threadIdx.x; int bx = blockIdx.x; asm volatile("" : "+v"(tx), "+s"(bx));
; DI unsigned xb_ld(unsigned* p)              { return __hip_atomic_load(p, __ATOMIC_RELAXED, __HIP_MEMORY_SCOPE_AGENT); }
; #define XB_SPIN(cond, bar) do { unsigned _sp = 0; while (cond) { __builtin_amdgcn_s_sleep(1); \
;     if ((++_sp & 255u) == 0u) { if (xb_ld(&(bar)[XB_TMO])) break; if (_sp > XB_SPIN_CAP) { atomicAdd(&(bar)[XB_TMO], 1u); break; } } } } while (0)
; template <int MODE>
; DI void headnorm_phase(const Params& p, const bf16_t* __restrict__ A0, const bf16_t* __restrict__ A1, const bf16_t* __restrict__ G, const float* gain, float lam, float outscale) {
;     OPAQUE_IDS
;     const int lane = tx & 63, gw = bx * 8 + (tx >> 6), nw = gridDim.x * 8;
;     bf16_t* H = (bf16_t*)(p.ws + WS_H); const int hh = lane >> 3, d0 = (lane & 7) * 16;
;     for (int row = gw; row < T; row += nw) {
; DI void xcd_barrier(const XcdBarrier& b) {
;     ...
;             XB_SPIN(xb_ld(&bar[XB_XGEN(b.x)]) == gen, bar);
;             __builtin_amdgcn_fence(__ATOMIC_ACQUIRE, "agent");
;             asm volatile("s_waitcnt vmcnt(0)" ::: "memory");
;         }
;     }
;     __syncthreads();
.LBB0_2495:
	s_or_b64 exec, exec, s[0:1]
	v_mov_b32_e32 v2, v252
	s_mov_b32 s0, s87
	s_waitcnt lgkmcnt(0)
	s_barrier
	v_readfirstlane_b32 s98, v252
	s_nop 3
	s_lshr_b32 s98, s98, 6

; #define OPAQUE_IDS int tx = threadIdx.x; int bx = blockIdx.x; asm volatile("" : "+v"(tx), "+s"(bx));
; DI float bflo(unsigned w) { return __uint_as_float(w << 16); }
; DI float bfhi(unsigned w) { return __uint_as_float(w & 0xffff0000u); }
; template <int MODE>
; DI void headnorm_phase(const Params& p, const bf16_t* __restrict__ A0, const bf16_t* __restrict__ A1, const bf16_t* __restrict__ G, const float* gain, float lam, float outscale) {
;     OPAQUE_IDS
;     const int lane = tx & 63, gw = bx * 8 + (tx >> 6), nw = gridDim.x * 8;
;     bf16_t* H = (bf16_t*)(p.ws + WS_H); const int hh = lane >> 3, d0 = (lane & 7) * 16;
;     for (int row = gw; row < T; row += nw) {
;         float x[16];
; #pragma unroll
;         for (int c = 0; c < 2; ++c) {
;             u32x4 a, b2;
;             if (MODE == 0) { a = *(const u32x4*)(A0 + (size_t)row * 2048 + hh * 256 + d0 + c * 8); b2 = *(const u32x4*)(A0 + (size_t)row * 2048 + hh * 256 + 128 + d0 + c * 8); }
;             else { a = *(const u32x4*)(A0 + (size_t)row * D + hh * 128 + d0 + c * 8); b2 = *(const u32x4*)(A1 + (size_t)row * D + hh * 128 + d0 + c * 8); }
;             const float s = MODE == 0 ? -lam : 1.f;
;             x[c * 8 + 0] = bflo(a.x) + s * bflo(b2.x); x[c * 8 + 1] = bfhi(a.x) + s * bfhi(b2.x); x[c * 8 + 2] = bflo(a.y) + s * bflo(b2.y); x[c * 8 + 3] = bfhi(a.y) + s * bfhi(b2.y);
;             x[c * 8 + 4] = bflo(a.z) + s * bflo(b2.z); x[c * 8 + 5] = bfhi(a.z) + s * bfhi(b2.z); x[c * 8 + 6] = bflo(a.w) + s * bflo(b2.w); x[c * 8 + 7] = bfhi(a.w) + s * bfhi(b2.w);
;         }
;         float ss = 0.f;
; #pragma unroll
;         for (int e = 0; e < 16; ++e) ss += x[e] * x[e];
;         ss += __shfl_xor(ss, 1); ss += __shfl_xor(ss, 2); ss += __shfl_xor(ss, 4);
.Lstg_21_done:
	s_lshl_b32 s0, s0, 3
	v_ashrrev_i32_e32 v0, 6, v2
	v_add_u32_e32 v18, s0, v0
	s_movk_i32 s1, 0x4800
	v_cmp_gt_i32_e32 vcc, s1, v18
	s_and_saveexec_b64 s[2:3], vcc
	s_cbranch_execz .LBB0_2498
	v_mbcnt_hi_u32_b32 v1, -1, v253
	v_and_b32_e32 v4, 64, v1
	v_xor_b32_e32 v3, 1, v1
	v_add_u32_e32 v4, 64, v4
	v_cmp_lt_i32_e32 vcc, v3, v4
	s_ashr_i32 s1, s0, 31
	v_readlane_b32 s36, v254, 23
	v_cndmask_b32_e32 v3, v1, v3, vcc
	v_lshlrev_b32_e32 v19, 2, v3
	v_xor_b32_e32 v3, 2, v1
	v_cmp_lt_i32_e32 vcc, v3, v4
	v_mov_b32_e32 v5, 0
	v_readlane_b32 s42, v254, 29
	v_cndmask_b32_e32 v3, v1, v3, vcc
	v_lshlrev_b32_e32 v20, 2, v3
	v_xor_b32_e32 v3, 4, v1
	v_cmp_lt_i32_e32 vcc, v3, v4
	v_readlane_b32 s43, v254, 30
	s_ashr_i32 s31, s30, 31
	v_cndmask_b32_e32 v1, v1, v3, vcc
	v_lshlrev_b32_e32 v21, 2, v1
	v_lshlrev_b32_e32 v1, 6, v2
	v_and_b32_e32 v4, 0x1c0, v1
	v_ashrrev_i32_e32 v1, 31, v0
	v_lshl_add_u64 v[0:1], v[0:1], 0, s[0:1]
	v_lshlrev_b32_e32 v3, 5, v2
	v_and_b32_e32 v2, 7, v2
	v_lshlrev_b64 v[0:1], 11, v[0:1]
	v_and_b32_e32 v3, 0x700, v3
	v_lshlrev_b32_e32 v2, 5, v2
	v_or3_b32 v0, v0, v3, v2
	v_lshl_add_u64 v[0:1], s[68:69], 0, v[0:1]
	s_mov_b64 s[0:1], 0x146da010
	s_mov_b32 s8, 0xedfffff0
	s_mov_b32 s10, 0xfdbffff0
	v_lshl_add_u64 v[12:13], s[42:43], 0, v[4:5]
	v_lshl_add_u64 v[14:15], v[0:1], 0, s[0:1]
	s_lshl_b64 s[4:5], s[30:31], 11
	s_mov_b64 s[6:7], 0
	s_mov_b32 s9, -1
	s_mov_b32 s11, -1
	s_mov_b32 s12, 0xfdc00000
	v_mov_b32_e32 v22, 0x358637bd
	s_mov_b32 s13, 0x800000
	s_movk_i32 s14, 0x47ff
	v_readlane_b32 s37, v254, 24
	v_readlane_b32 s38, v254, 25
	v_readlane_b32 s39, v254, 26
	v_readlane_b32 s40, v254, 27
	v_readlane_b32 s41, v254, 28
	v_readlane_b32 s44, v254, 31
	v_readlane_b32 s45, v254, 32
	v_readlane_b32 s46, v254, 33
	v_readlane_b32 s47, v254, 34
	v_readlane_b32 s48, v254, 35
	v_readlane_b32 s49, v254, 36
	v_readlane_b32 s50, v254, 37
	v_readlane_b32 s51, v254, 38

; #define OPAQUE_IDS int tx = threadIdx.x; int bx = blockIdx.x; asm volatile("" : "+v"(tx), "+s"(bx));
; DI float wave_sum(float v) {
;     v += __shfl_xor(v, 32); v += __shfl_xor(v, 16); v += __shfl_xor(v, 8); v += __shfl_xor(v, 4); v += __shfl_xor(v, 2); v += __shfl_xor(v, 1);
;     return v;
; DI void norm_phase(const Params& p, int layer, int which, bool lat_only, const float* __restrict__ part, int npart, int srcmode) {
;     OPAQUE_IDS
;     const int lane = tx & 63, gw = bx * 8 + (tx >> 6);
;     const float* gain = p.in[6] + ((size_t)layer * 2 + which) * D; const float* mod = (const float*)(p.ws + WS_MOD) + (size_t)layer * 9 * 6144;
;     bf16_t* H = (bf16_t*)(p.ws + WS_H);
;     f32x4 gm[4], sh[4]; int cur_ci = -1;
;     const int nw = gridDim.x * 8;
;     for (int vw = gw; vw < NB * 256; vw += nw)
;     for (int i0 = 0; i0 < 9; i0 += 3) {
;         const int r0 = (vw >> 8) * LT + (vw & 255) + 256 * i0;
;         f32x4 v[3][4]; float ss[3]; bool ok[3];
; #pragma unroll
;         for (int q = 0; q < 3; ++q) {
;             const int row = r0 + 256 * q; const int b = row / LT, pos = row - b * LT;
;             ok[q] = !(lat_only && pos < LC); ss[q] = 0.f;
;             if (ok[q]) {
;                 float* x = resid_row(p, row);
;                 const float* xs = (srcmode == 1 || (srcmode == 2 && pos < LC)) ? (pos < LC ? p.in[2] + ((size_t)(b * LC + pos)) * D : p.in[0] + ((size_t)(b * LL + pos - LC)) * D) : x;
; #pragma unroll
;                 for (int j = 0; j < 4; ++j) v[q][j] = *(const f32x4*)(xs + j * 256 + lane * 4);
;                 if (part != nullptr && pos < LC) {
;                     f32x4 a[4];
; #pragma unroll
;                     for (int j = 0; j < 4; ++j) a[j] = (f32x4){0.f, 0.f, 0.f, 0.f};
;                     const float* pp = part + (size_t)(b * LC + pos) * D + lane * 4;
;                     for (int s = 0; s < npart; ++s) {
; #pragma unroll
;                         for (int j = 0; j < 4; ++j) a[j] += *(const f32x4*)(pp + (size_t)s * NB * LC * D + j * 256); }
.Lstg_23_done:
	s_nop 0
	v_ashrrev_i32_e32 v1, 6, v0
	v_lshl_add_u32 v81, s0, 3, v1
	s_movk_i32 s0, 0x800
	v_cmp_gt_i32_e32 vcc, s0, v81
	s_and_saveexec_b64 s[6:7], vcc
	s_cbranch_execz .LBB0_2744
	v_lshlrev_b32_e32 v0, 2, v0
	v_and_b32_e32 v80, 0xfc, v0
	v_mbcnt_hi_u32_b32 v0, -1, v253
	v_and_b32_e32 v2, 64, v0
	v_xor_b32_e32 v1, 32, v0
	v_add_u32_e32 v2, 64, v2
	v_cmp_lt_i32_e32 vcc, v1, v2
	s_add_u32 s0, s60, 0x5000
	s_addc_u32 s1, s61, 0
	v_cndmask_b32_e32 v1, v0, v1, vcc
	v_lshlrev_b32_e32 v89, 2, v1
	v_xor_b32_e32 v1, 16, v0
	v_cmp_lt_i32_e32 vcc, v1, v2
	v_mov_b32_e32 v83, 0
	v_lshlrev_b32_e32 v82, 2, v80
	v_cndmask_b32_e32 v1, v0, v1, vcc
	v_lshlrev_b32_e32 v93, 2, v1
	v_xor_b32_e32 v1, 8, v0
	v_cmp_lt_i32_e32 vcc, v1, v2
	v_or_b32_e32 v88, 0x100, v80
	v_lshl_add_u64 v[84:85], s[96:97], 0, v[82:83]
	v_cndmask_b32_e32 v1, v0, v1, vcc
	v_lshlrev_b32_e32 v97, 2, v1
	v_xor_b32_e32 v1, 4, v0
	v_cmp_lt_i32_e32 vcc, v1, v2
	v_lshl_add_u64 v[86:87], s[0:1], 0, v[82:83]
	v_lshlrev_b32_e32 v82, 2, v88
	v_cndmask_b32_e32 v1, v0, v1, vcc
	v_lshlrev_b32_e32 v120, 2, v1
	v_xor_b32_e32 v1, 2, v0
	v_cmp_lt_i32_e32 vcc, v1, v2
	v_or_b32_e32 v92, 0x200, v80
	v_lshl_add_u64 v[90:91], s[0:1], 0, v[82:83]
	v_cndmask_b32_e32 v1, v0, v1, vcc
	v_lshlrev_b32_e32 v121, 2, v1
	v_xor_b32_e32 v1, 1, v0
	v_lshlrev_b32_e32 v82, 2, v92
	v_or_b32_e32 v96, 0x300, v80
	v_cmp_lt_i32_e32 vcc, v1, v2
	v_lshl_add_u64 v[94:95], s[0:1], 0, v[82:83]
	v_lshlrev_b32_e32 v82, 2, v96
	v_cndmask_b32_e32 v0, v0, v1, vcc
	s_add_u32 s8, s68, 0x86f000
	v_lshl_add_u64 v[98:99], s[0:1], 0, v[82:83]
	v_lshlrev_b32_e32 v82, 1, v80
	v_mov_b32_e32 v107, -1
	v_lshlrev_b32_e32 v122, 2, v0
	s_addc_u32 s9, s69, 0
	s_movk_i32 s31, 0x100
	v_lshl_add_u64 v[100:101], s[16:17], 0, v[82:83]
	s_mov_b64 s[10:11], 0
	s_movk_i32 s34, 0xff
	s_mov_b32 s35, 0x38e38e39
	s_movk_i32 s36, 0xf700
	s_movk_i32 s37, 0xff00
	s_mov_b32 s38, 0x800000
	s_mov_b32 s39, 0x1000000
	s_mov_b32 s40, 0x1800000
	s_mov_b64 s[12:13], 0x1000
	v_mov_b32_e32 v123, 0x358637bd
	s_movk_i32 s41, 0x7ff
	s_branch .LBB0_2672

; #define OPAQUE_IDS int tx = threadIdx.x; int bx = blockIdx.x; asm volatile("" : "+v"(tx), "+s"(bx));
; DI float wave_sum(float v) {
;     v += __shfl_xor(v, 32); v += __shfl_xor(v, 16); v += __shfl_xor(v, 8); v += __shfl_xor(v, 4); v += __shfl_xor(v, 2); v += __shfl_xor(v, 1);
;     return v;
; DI void norm_phase(const Params& p, int layer, int which, bool lat_only, const float* __restrict__ part, int npart, int srcmode) {
;     OPAQUE_IDS
;     const int lane = tx & 63, gw = bx * 8 + (tx >> 6);
;     const float* gain = p.in[6] + ((size_t)layer * 2 + which) * D; const float* mod = (const float*)(p.ws + WS_MOD) + (size_t)layer * 9 * 6144;
;     bf16_t* H = (bf16_t*)(p.ws + WS_H);
;     f32x4 gm[4], sh[4]; int cur_ci = -1;
;     const int nw = gridDim.x * 8;
;     for (int vw = gw; vw < NB * 256; vw += nw)
;     for (int i0 = 0; i0 < 9; i0 += 3) {
;         const int r0 = (vw >> 8) * LT + (vw & 255) + 256 * i0;
;         f32x4 v[3][4]; float ss[3]; bool ok[3];
; #pragma unroll
;         for (int q = 0; q < 3; ++q) {
;             const int row = r0 + 256 * q; const int b = row / LT, pos = row - b * LT;
;             ok[q] = !(lat_only && pos < LC); ss[q] = 0.f;
;             if (ok[q]) {
;                 float* x = resid_row(p, row);
;                 const float* xs = (srcmode == 1 || (srcmode == 2 && pos < LC)) ? (pos < LC ? p.in[2] + ((size_t)(b * LC + pos)) * D : p.in[0] + ((size_t)(b * LL + pos - LC)) * D) : x;
; #pragma unroll
;                 for (int j = 0; j < 4; ++j) v[q][j] = *(const f32x4*)(xs + j * 256 + lane * 4);
;                 if (part != nullptr && pos < LC) {
;                     f32x4 a[4];
; #pragma unroll
;                     for (int j = 0; j < 4; ++j) a[j] = (f32x4){0.f, 0.f, 0.f, 0.f};
;                     const float* pp = part + (size_t)(b * LC + pos) * D + lane * 4;
;                     for (int s = 0; s < npart; ++s) {
; #pragma unroll
;                         for (int j = 0; j < 4; ++j) a[j] += *(const f32x4*)(pp + (size_t)s * NB * LC * D + j * 256); }
.Lstg_26_done:
	s_load_dword s1, s[2:3], 0x10
	s_nop 0
	s_load_dword s2, s[2:3], 0x0
	v_ashrrev_i32_e32 v1, 6, v0
	v_lshl_add_u32 v81, s0, 3, v1
	s_waitcnt lgkmcnt(0)
	s_lshr_b32 s0, s1, 16
	s_cmp_lg_u32 s0, 0
	s_cselect_b64 s[0:1], -1, 0
	s_cmp_lg_u64 s[0:1], 0
	s_addc_u32 s26, s2, 0
	s_movk_i32 s0, 0x800
	s_lshl_b32 s62, s26, 3
	v_cmp_gt_i32_e32 vcc, s0, v81
	s_and_saveexec_b64 s[6:7], vcc
	s_cbranch_execz .LBB0_3072
	v_lshlrev_b32_e32 v0, 2, v0
	v_and_b32_e32 v80, 0xfc, v0
	v_mbcnt_hi_u32_b32 v0, -1, v253
	v_and_b32_e32 v2, 64, v0
	v_xor_b32_e32 v1, 32, v0
	v_add_u32_e32 v2, 64, v2
	v_cmp_lt_i32_e32 vcc, v1, v2
	s_add_u32 s0, s60, 0x6000
	s_addc_u32 s1, s61, 0
	v_cndmask_b32_e32 v1, v0, v1, vcc
	v_lshlrev_b32_e32 v89, 2, v1
	v_xor_b32_e32 v1, 16, v0
	v_cmp_lt_i32_e32 vcc, v1, v2
	v_mov_b32_e32 v83, 0
	v_lshlrev_b32_e32 v82, 2, v80
	v_cndmask_b32_e32 v1, v0, v1, vcc
	v_lshlrev_b32_e32 v93, 2, v1
	v_xor_b32_e32 v1, 8, v0
	v_cmp_lt_i32_e32 vcc, v1, v2
	v_or_b32_e32 v88, 0x100, v80
	v_lshl_add_u64 v[84:85], s[28:29], 0, v[82:83]
	v_cndmask_b32_e32 v1, v0, v1, vcc
	v_lshlrev_b32_e32 v97, 2, v1
	v_xor_b32_e32 v1, 4, v0
	v_cmp_lt_i32_e32 vcc, v1, v2
	v_lshl_add_u64 v[86:87], s[0:1], 0, v[82:83]
	v_lshlrev_b32_e32 v82, 2, v88
	v_cndmask_b32_e32 v1, v0, v1, vcc
	v_lshlrev_b32_e32 v120, 2, v1
	v_xor_b32_e32 v1, 2, v0
	v_cmp_lt_i32_e32 vcc, v1, v2
	v_or_b32_e32 v92, 0x200, v80
	v_lshl_add_u64 v[90:91], s[0:1], 0, v[82:83]
	v_cndmask_b32_e32 v1, v0, v1, vcc
	v_lshlrev_b32_e32 v121, 2, v1
	v_xor_b32_e32 v1, 1, v0
	v_lshlrev_b32_e32 v82, 2, v92
	v_or_b32_e32 v96, 0x300, v80
	v_cmp_lt_i32_e32 vcc, v1, v2
	v_lshl_add_u64 v[94:95], s[0:1], 0, v[82:83]
	v_lshlrev_b32_e32 v82, 2, v96
	s_add_u32 s8, s68, 0x8a2000
	v_cndmask_b32_e32 v0, v0, v1, vcc
	v_lshl_add_u64 v[98:99], s[0:1], 0, v[82:83]
	v_lshlrev_b32_e32 v82, 1, v80
	s_addc_u32 s9, s69, 0
	v_mov_b32_e32 v109, -1
	v_lshlrev_b32_e32 v122, 2, v0
	s_movk_i32 s30, 0x100
	v_lshl_add_u64 v[100:101], s[16:17], 0, v[82:83]
	s_mov_b64 s[10:11], 0
	s_movk_i32 s31, 0xff
	s_mov_b32 s34, 0x38e38e39
	s_movk_i32 s35, 0xf700
	s_movk_i32 s36, 0xff00
	s_mov_b32 s37, 0x800000
	s_mov_b32 s38, 0x1000000
	s_mov_b32 s39, 0x1800000
	s_brev_b32 s40, 64
	s_mov_b32 s41, 0x2800000
	s_mov_b32 s42, 0x3000000
	s_mov_b32 s43, 0x3800000
	s_mov_b64 s[12:13], 0x1000
	v_mov_b32_e32 v123, 0x358637bd
	s_movk_i32 s44, 0x7ff
	s_branch .LBB0_3000

; #define OPAQUE_IDS int tx = threadIdx.x; int bx = blockIdx.x; asm volatile("" : "+v"(tx), "+s"(bx));
; DI float wave_sum(float v) {
;     v += __shfl_xor(v, 32); v += __shfl_xor(v, 16); v += __shfl_xor(v, 8); v += __shfl_xor(v, 4); v += __shfl_xor(v, 2); v += __shfl_xor(v, 1);
;     return v;
; DI void norm_phase(const Params& p, int layer, int which, bool lat_only, const float* __restrict__ part, int npart, int srcmode) {
;     OPAQUE_IDS
;     const int lane = tx & 63, gw = bx * 8 + (tx >> 6);
;     const float* gain = p.in[6] + ((size_t)layer * 2 + which) * D; const float* mod = (const float*)(p.ws + WS_MOD) + (size_t)layer * 9 * 6144;
;     bf16_t* H = (bf16_t*)(p.ws + WS_H);
;     f32x4 gm[4], sh[4]; int cur_ci = -1;
;     const int nw = gridDim.x * 8;
;     for (int vw = gw; vw < NB * 256; vw += nw)
;     for (int i0 = 0; i0 < 9; i0 += 3) {
;         const int r0 = (vw >> 8) * LT + (vw & 255) + 256 * i0;
;         f32x4 v[3][4]; float ss[3]; bool ok[3];
; #pragma unroll
;         for (int q = 0; q < 3; ++q) {
;             const int row = r0 + 256 * q; const int b = row / LT, pos = row - b * LT;
;             ok[q] = !(lat_only && pos < LC); ss[q] = 0.f;
;             if (ok[q]) {
;                 float* x = resid_row(p, row);
;                 const float* xs = (srcmode == 1 || (srcmode == 2 && pos < LC)) ? (pos < LC ? p.in[2] + ((size_t)(b * LC + pos)) * D : p.in[0] + ((size_t)(b * LL + pos - LC)) * D) : x;
; #pragma unroll
;                 for (int j = 0; j < 4; ++j) v[q][j] = *(const f32x4*)(xs + j * 256 + lane * 4);
.Lstg_31_done:
	s_nop 0
	v_ashrrev_i32_e32 v1, 6, v0
	v_lshl_add_u32 v81, s0, 3, v1
	s_movk_i32 s0, 0x800
	v_cmp_gt_i32_e32 vcc, s0, v81
	s_and_saveexec_b64 s[4:5], vcc
	s_cbranch_execz .LBB0_3618
	v_lshlrev_b32_e32 v0, 2, v0
	v_and_b32_e32 v80, 0xfc, v0
	v_mbcnt_hi_u32_b32 v0, -1, v253
	v_and_b32_e32 v2, 64, v0
	v_xor_b32_e32 v1, 32, v0
	v_add_u32_e32 v2, 64, v2
	v_cmp_lt_i32_e32 vcc, v1, v2
	s_add_u32 s0, s60, 0x7000
	v_mov_b32_e32 v83, 0
	v_cndmask_b32_e32 v1, v0, v1, vcc
	v_lshlrev_b32_e32 v87, 2, v1
	v_xor_b32_e32 v1, 16, v0
	v_cmp_lt_i32_e32 vcc, v1, v2
	v_or_b32_e32 v86, 0x100, v80
	s_addc_u32 s1, s61, 0
	v_cndmask_b32_e32 v1, v0, v1, vcc
	v_lshlrev_b32_e32 v91, 2, v1
	v_xor_b32_e32 v1, 8, v0
	v_cmp_lt_i32_e32 vcc, v1, v2
	v_or_b32_e32 v90, 0x200, v80
	v_lshlrev_b32_e32 v82, 2, v80
	v_cndmask_b32_e32 v1, v0, v1, vcc
	v_lshlrev_b32_e32 v95, 2, v1
	v_xor_b32_e32 v1, 4, v0
	v_cmp_lt_i32_e32 vcc, v1, v2
	v_or_b32_e32 v94, 0x300, v80
	s_add_u32 s6, s68, 0x8a5000
	v_cndmask_b32_e32 v1, v0, v1, vcc
	v_lshlrev_b32_e32 v114, 2, v1
	v_xor_b32_e32 v1, 2, v0
	v_cmp_lt_i32_e32 vcc, v1, v2
	v_lshl_add_u64 v[84:85], s[0:1], 0, v[82:83]
	v_lshl_add_u64 v[98:99], s[66:67], 0, v[82:83]
	v_cndmask_b32_e32 v1, v0, v1, vcc
	v_lshlrev_b32_e32 v115, 2, v1
	v_xor_b32_e32 v1, 1, v0
	v_cmp_lt_i32_e32 vcc, v1, v2
	v_lshlrev_b32_e32 v82, 1, v80
	v_mov_b32_e32 v118, -1
	v_cndmask_b32_e32 v0, v0, v1, vcc
	v_lshlrev_b32_e32 v116, 2, v0
	v_lshlrev_b32_e32 v0, 2, v86
	v_mov_b32_e32 v1, v83
	v_lshl_add_u64 v[88:89], s[0:1], 0, v[0:1]
	v_lshlrev_b32_e32 v0, 2, v90
	v_lshl_add_u64 v[92:93], s[0:1], 0, v[0:1]
	v_lshlrev_b32_e32 v0, 2, v94
	s_addc_u32 s7, s69, 0
	v_lshl_add_u64 v[96:97], s[0:1], 0, v[0:1]
	v_lshl_add_u64 v[100:101], s[16:17], 0, v[82:83]
	s_mov_b64 s[8:9], 0
	s_movk_i32 s22, 0xff
	s_mov_b32 s23, 0x38e38e39
	s_movk_i32 s24, 0xf700
	s_movk_i32 s25, 0xff00
	s_mov_b64 s[10:11], 0x1000
	v_mov_b32_e32 v117, 0x358637bd
	s_mov_b32 s30, 0x800000
	s_movk_i32 s31, 0x7ff
	s_branch .LBB0_3565
